# v41: v39 + final RMSNorm step straight-lined for its 16 rows per wave: gains loaded once, row loads two rows ahead, counted vmcnt, stores not waited for
# speedup vs baseline: 1.0128x; 1.0128x over previous
.LBB0_29:
	s_cmp_lg_u32 s72, 0x800
	s_cbranch_scc1 .Lfn_orig
	global_load_dwordx4 v[50:53], v[2:3], off
	global_load_dwordx4 v[54:57], v[2:3], off offset:16
	global_load_dwordx4 v[58:61], v[2:3], off offset:32
	global_load_dwordx4 v[62:65], v[2:3], off offset:48
	global_load_dwordx4 v[66:69], v[6:7], off offset:-16
	global_load_dwordx4 v[70:73], v[6:7], off
	v_lshl_add_u64 v[6:7], v[6:7], 0, s[16:17]
	global_load_dwordx4 v[74:77], v[6:7], off offset:-16
	global_load_dwordx4 v[78:81], v[6:7], off
	v_lshl_add_u64 v[6:7], v[6:7], 0, s[16:17]
	global_load_dwordx4 v[82:85], v[6:7], off offset:-16
	global_load_dwordx4 v[86:89], v[6:7], off
	v_lshl_add_u64 v[6:7], v[6:7], 0, s[16:17]
	s_waitcnt vmcnt(4)
	v_lshlrev_b32_e32 v26, 16, v66
	v_and_b32_e32 v27, 0xffff0000, v66
	v_lshlrev_b32_e32 v28, 16, v67
	v_and_b32_e32 v29, 0xffff0000, v67
	v_lshlrev_b32_e32 v30, 16, v68
	v_and_b32_e32 v31, 0xffff0000, v68
	v_lshlrev_b32_e32 v32, 16, v69
	v_and_b32_e32 v33, 0xffff0000, v69
	v_lshlrev_b32_e32 v34, 16, v70
	v_and_b32_e32 v35, 0xffff0000, v70
	v_lshlrev_b32_e32 v36, 16, v71
	v_and_b32_e32 v37, 0xffff0000, v71
	v_lshlrev_b32_e32 v38, 16, v72
	v_and_b32_e32 v39, 0xffff0000, v72
	v_lshlrev_b32_e32 v40, 16, v73
	v_and_b32_e32 v41, 0xffff0000, v73
	v_pk_mul_f32 v[42:43], v[26:27], v[26:27]
	v_add_f32_e32 v1, v42, v43
	v_pk_mul_f32 v[42:43], v[28:29], v[28:29]
	v_add_f32_e32 v1, v42, v1
	v_add_f32_e32 v1, v43, v1
	v_pk_mul_f32 v[42:43], v[30:31], v[30:31]
	v_add_f32_e32 v1, v42, v1
	v_add_f32_e32 v1, v43, v1
	v_pk_mul_f32 v[42:43], v[32:33], v[32:33]
	v_add_f32_e32 v1, v42, v1
	v_add_f32_e32 v1, v43, v1
	v_pk_mul_f32 v[42:43], v[34:35], v[34:35]
	v_add_f32_e32 v1, v42, v1
	v_add_f32_e32 v1, v43, v1
	v_pk_mul_f32 v[42:43], v[36:37], v[36:37]
	v_add_f32_e32 v1, v42, v1
	v_add_f32_e32 v1, v43, v1
	v_pk_mul_f32 v[42:43], v[38:39], v[38:39]
	v_add_f32_e32 v1, v42, v1
	v_add_f32_e32 v1, v43, v1
	v_pk_mul_f32 v[42:43], v[40:41], v[40:41]
	v_add_f32_e32 v1, v42, v1
	v_add_f32_e32 v1, v43, v1
	ds_bpermute_b32 v16, v8, v1
	s_waitcnt lgkmcnt(0)
	v_add_f32_e32 v1, v1, v16
	ds_bpermute_b32 v16, v9, v1
	s_waitcnt lgkmcnt(0)
	v_add_f32_e32 v1, v1, v16
	ds_bpermute_b32 v16, v10, v1
	s_waitcnt lgkmcnt(0)
	v_add_f32_e32 v1, v1, v16
	ds_bpermute_b32 v16, v11, v1
	s_waitcnt lgkmcnt(0)
	v_add_f32_e32 v1, v1, v16
	ds_bpermute_b32 v16, v12, v1
	s_waitcnt lgkmcnt(0)
	v_add_f32_e32 v1, v1, v16
	ds_bpermute_b32 v16, v13, v1
	s_waitcnt lgkmcnt(0)
	v_add_f32_e32 v1, v1, v16
	v_fmamk_f32 v1, v1, 0x3a800000, v194
	v_mul_f32_e32 v16, 0x4b800000, v1
	v_cmp_gt_f32_e32 vcc, s83, v1
	s_nop 1
	v_cndmask_b32_e32 v1, v1, v16, vcc
	v_rsq_f32_e32 v1, v1
	s_nop 0
	v_mul_f32_e32 v16, 0x45800000, v1
	v_cndmask_b32_e32 v48, v1, v16, vcc
	v_pk_mul_f32 v[44:45], v[48:49], v[26:27] op_sel_hi:[0,1]
	v_pk_mul_f32 v[46:47], v[48:49], v[28:29] op_sel_hi:[0,1]
	v_pk_mul_f32 v[44:45], v[50:51], v[44:45]
	v_pk_mul_f32 v[46:47], v[52:53], v[46:47]
	global_store_dwordx4 v[4:5], v[44:47], off offset:-48
	v_pk_mul_f32 v[90:91], v[48:49], v[30:31] op_sel_hi:[0,1]
	v_pk_mul_f32 v[92:93], v[48:49], v[32:33] op_sel_hi:[0,1]
	v_pk_mul_f32 v[90:91], v[54:55], v[90:91]
	v_pk_mul_f32 v[92:93], v[56:57], v[92:93]
	global_store_dwordx4 v[4:5], v[90:93], off offset:-32
	v_pk_mul_f32 v[44:45], v[48:49], v[34:35] op_sel_hi:[0,1]
	v_pk_mul_f32 v[46:47], v[48:49], v[36:37] op_sel_hi:[0,1]
	v_pk_mul_f32 v[44:45], v[58:59], v[44:45]
	v_pk_mul_f32 v[46:47], v[60:61], v[46:47]
	global_store_dwordx4 v[4:5], v[44:47], off offset:-16
	v_pk_mul_f32 v[90:91], v[48:49], v[38:39] op_sel_hi:[0,1]
	v_pk_mul_f32 v[92:93], v[48:49], v[40:41] op_sel_hi:[0,1]
	v_pk_mul_f32 v[90:91], v[62:63], v[90:91]
	v_pk_mul_f32 v[92:93], v[64:65], v[92:93]
	global_store_dwordx4 v[4:5], v[90:93], off
	v_lshl_add_u64 v[4:5], v[4:5], 0, s[14:15]
	global_load_dwordx4 v[66:69], v[6:7], off offset:-16
	global_load_dwordx4 v[70:73], v[6:7], off
	v_lshl_add_u64 v[6:7], v[6:7], 0, s[16:17]
	s_waitcnt vmcnt(8)
	v_lshlrev_b32_e32 v26, 16, v74
	v_and_b32_e32 v27, 0xffff0000, v74
	v_lshlrev_b32_e32 v28, 16, v75
	v_and_b32_e32 v29, 0xffff0000, v75
	v_lshlrev_b32_e32 v30, 16, v76
	v_and_b32_e32 v31, 0xffff0000, v76
	v_lshlrev_b32_e32 v32, 16, v77
	v_and_b32_e32 v33, 0xffff0000, v77
	v_lshlrev_b32_e32 v34, 16, v78
	v_and_b32_e32 v35, 0xffff0000, v78
	v_lshlrev_b32_e32 v36, 16, v79
	v_and_b32_e32 v37, 0xffff0000, v79
	v_lshlrev_b32_e32 v38, 16, v80
	v_and_b32_e32 v39, 0xffff0000, v80
	v_lshlrev_b32_e32 v40, 16, v81
	v_and_b32_e32 v41, 0xffff0000, v81
	v_pk_mul_f32 v[42:43], v[26:27], v[26:27]
	v_add_f32_e32 v1, v42, v43
	v_pk_mul_f32 v[42:43], v[28:29], v[28:29]
	v_add_f32_e32 v1, v42, v1
	v_add_f32_e32 v1, v43, v1
	v_pk_mul_f32 v[42:43], v[30:31], v[30:31]
	v_add_f32_e32 v1, v42, v1
	v_add_f32_e32 v1, v43, v1
	v_pk_mul_f32 v[42:43], v[32:33], v[32:33]
	v_add_f32_e32 v1, v42, v1
	v_add_f32_e32 v1, v43, v1
	v_pk_mul_f32 v[42:43], v[34:35], v[34:35]
	v_add_f32_e32 v1, v42, v1
	v_add_f32_e32 v1, v43, v1
	v_pk_mul_f32 v[42:43], v[36:37], v[36:37]
	v_add_f32_e32 v1, v42, v1
	v_add_f32_e32 v1, v43, v1
	v_pk_mul_f32 v[42:43], v[38:39], v[38:39]
	v_add_f32_e32 v1, v42, v1
	v_add_f32_e32 v1, v43, v1
	v_pk_mul_f32 v[42:43], v[40:41], v[40:41]
	v_add_f32_e32 v1, v42, v1
	v_add_f32_e32 v1, v43, v1
	ds_bpermute_b32 v16, v8, v1
	s_waitcnt lgkmcnt(0)
	v_add_f32_e32 v1, v1, v16
	ds_bpermute_b32 v16, v9, v1
	s_waitcnt lgkmcnt(0)
	v_add_f32_e32 v1, v1, v16
	ds_bpermute_b32 v16, v10, v1
	s_waitcnt lgkmcnt(0)
	v_add_f32_e32 v1, v1, v16
	ds_bpermute_b32 v16, v11, v1
	s_waitcnt lgkmcnt(0)
	v_add_f32_e32 v1, v1, v16
	ds_bpermute_b32 v16, v12, v1
	s_waitcnt lgkmcnt(0)
	v_add_f32_e32 v1, v1, v16
	ds_bpermute_b32 v16, v13, v1
	s_waitcnt lgkmcnt(0)
	v_add_f32_e32 v1, v1, v16
	v_fmamk_f32 v1, v1, 0x3a800000, v194
	v_mul_f32_e32 v16, 0x4b800000, v1
	v_cmp_gt_f32_e32 vcc, s83, v1
	s_nop 1
	v_cndmask_b32_e32 v1, v1, v16, vcc
	v_rsq_f32_e32 v1, v1
	s_nop 0
	v_mul_f32_e32 v16, 0x45800000, v1
	v_cndmask_b32_e32 v48, v1, v16, vcc
	v_pk_mul_f32 v[44:45], v[48:49], v[26:27] op_sel_hi:[0,1]
	v_pk_mul_f32 v[46:47], v[48:49], v[28:29] op_sel_hi:[0,1]
	v_pk_mul_f32 v[44:45], v[50:51], v[44:45]
	v_pk_mul_f32 v[46:47], v[52:53], v[46:47]
	global_store_dwordx4 v[4:5], v[44:47], off offset:-48
	v_pk_mul_f32 v[90:91], v[48:49], v[30:31] op_sel_hi:[0,1]
	v_pk_mul_f32 v[92:93], v[48:49], v[32:33] op_sel_hi:[0,1]
	v_pk_mul_f32 v[90:91], v[54:55], v[90:91]
	v_pk_mul_f32 v[92:93], v[56:57], v[92:93]
	global_store_dwordx4 v[4:5], v[90:93], off offset:-32
	v_pk_mul_f32 v[44:45], v[48:49], v[34:35] op_sel_hi:[0,1]
	v_pk_mul_f32 v[46:47], v[48:49], v[36:37] op_sel_hi:[0,1]
	v_pk_mul_f32 v[44:45], v[58:59], v[44:45]
	v_pk_mul_f32 v[46:47], v[60:61], v[46:47]
	global_store_dwordx4 v[4:5], v[44:47], off offset:-16
	v_pk_mul_f32 v[90:91], v[48:49], v[38:39] op_sel_hi:[0,1]
	v_pk_mul_f32 v[92:93], v[48:49], v[40:41] op_sel_hi:[0,1]
	v_pk_mul_f32 v[90:91], v[62:63], v[90:91]
	v_pk_mul_f32 v[92:93], v[64:65], v[92:93]
	global_store_dwordx4 v[4:5], v[90:93], off
	v_lshl_add_u64 v[4:5], v[4:5], 0, s[14:15]
	global_load_dwordx4 v[74:77], v[6:7], off offset:-16
	global_load_dwordx4 v[78:81], v[6:7], off
	v_lshl_add_u64 v[6:7], v[6:7], 0, s[16:17]
	s_waitcnt vmcnt(12)
	v_lshlrev_b32_e32 v26, 16, v82
	v_and_b32_e32 v27, 0xffff0000, v82
	v_lshlrev_b32_e32 v28, 16, v83
	v_and_b32_e32 v29, 0xffff0000, v83
	v_lshlrev_b32_e32 v30, 16, v84
	v_and_b32_e32 v31, 0xffff0000, v84
	v_lshlrev_b32_e32 v32, 16, v85
	v_and_b32_e32 v33, 0xffff0000, v85
	v_lshlrev_b32_e32 v34, 16, v86
	v_and_b32_e32 v35, 0xffff0000, v86
	v_lshlrev_b32_e32 v36, 16, v87
	v_and_b32_e32 v37, 0xffff0000, v87
	v_lshlrev_b32_e32 v38, 16, v88
	v_and_b32_e32 v39, 0xffff0000, v88
	v_lshlrev_b32_e32 v40, 16, v89
	v_and_b32_e32 v41, 0xffff0000, v89
	v_pk_mul_f32 v[42:43], v[26:27], v[26:27]
	v_add_f32_e32 v1, v42, v43
	v_pk_mul_f32 v[42:43], v[28:29], v[28:29]
	v_add_f32_e32 v1, v42, v1
	v_add_f32_e32 v1, v43, v1
	v_pk_mul_f32 v[42:43], v[30:31], v[30:31]
	v_add_f32_e32 v1, v42, v1
	v_add_f32_e32 v1, v43, v1
	v_pk_mul_f32 v[42:43], v[32:33], v[32:33]
	v_add_f32_e32 v1, v42, v1
	v_add_f32_e32 v1, v43, v1
	v_pk_mul_f32 v[42:43], v[34:35], v[34:35]
	v_add_f32_e32 v1, v42, v1
	v_add_f32_e32 v1, v43, v1
	v_pk_mul_f32 v[42:43], v[36:37], v[36:37]
	v_add_f32_e32 v1, v42, v1
	v_add_f32_e32 v1, v43, v1
	v_pk_mul_f32 v[42:43], v[38:39], v[38:39]
	v_add_f32_e32 v1, v42, v1
	v_add_f32_e32 v1, v43, v1
	v_pk_mul_f32 v[42:43], v[40:41], v[40:41]
	v_add_f32_e32 v1, v42, v1
	v_add_f32_e32 v1, v43, v1
	ds_bpermute_b32 v16, v8, v1
	s_waitcnt lgkmcnt(0)
	v_add_f32_e32 v1, v1, v16
	ds_bpermute_b32 v16, v9, v1
	s_waitcnt lgkmcnt(0)
	v_add_f32_e32 v1, v1, v16
	ds_bpermute_b32 v16, v10, v1
	s_waitcnt lgkmcnt(0)
	v_add_f32_e32 v1, v1, v16
	ds_bpermute_b32 v16, v11, v1
	s_waitcnt lgkmcnt(0)
	v_add_f32_e32 v1, v1, v16
	ds_bpermute_b32 v16, v12, v1
	s_waitcnt lgkmcnt(0)
	v_add_f32_e32 v1, v1, v16
	ds_bpermute_b32 v16, v13, v1
	s_waitcnt lgkmcnt(0)
	v_add_f32_e32 v1, v1, v16
	v_fmamk_f32 v1, v1, 0x3a800000, v194
	v_mul_f32_e32 v16, 0x4b800000, v1
	v_cmp_gt_f32_e32 vcc, s83, v1
	s_nop 1
	v_cndmask_b32_e32 v1, v1, v16, vcc
	v_rsq_f32_e32 v1, v1
	s_nop 0
	v_mul_f32_e32 v16, 0x45800000, v1
	v_cndmask_b32_e32 v48, v1, v16, vcc
	v_pk_mul_f32 v[44:45], v[48:49], v[26:27] op_sel_hi:[0,1]
	v_pk_mul_f32 v[46:47], v[48:49], v[28:29] op_sel_hi:[0,1]
	v_pk_mul_f32 v[44:45], v[50:51], v[44:45]
	v_pk_mul_f32 v[46:47], v[52:53], v[46:47]
	global_store_dwordx4 v[4:5], v[44:47], off offset:-48
	v_pk_mul_f32 v[90:91], v[48:49], v[30:31] op_sel_hi:[0,1]
	v_pk_mul_f32 v[92:93], v[48:49], v[32:33] op_sel_hi:[0,1]
	v_pk_mul_f32 v[90:91], v[54:55], v[90:91]
	v_pk_mul_f32 v[92:93], v[56:57], v[92:93]
	global_store_dwordx4 v[4:5], v[90:93], off offset:-32
	v_pk_mul_f32 v[44:45], v[48:49], v[34:35] op_sel_hi:[0,1]
	v_pk_mul_f32 v[46:47], v[48:49], v[36:37] op_sel_hi:[0,1]
	v_pk_mul_f32 v[44:45], v[58:59], v[44:45]
	v_pk_mul_f32 v[46:47], v[60:61], v[46:47]
	global_store_dwordx4 v[4:5], v[44:47], off offset:-16
	v_pk_mul_f32 v[90:91], v[48:49], v[38:39] op_sel_hi:[0,1]
	v_pk_mul_f32 v[92:93], v[48:49], v[40:41] op_sel_hi:[0,1]
	v_pk_mul_f32 v[90:91], v[62:63], v[90:91]
	v_pk_mul_f32 v[92:93], v[64:65], v[92:93]
	global_store_dwordx4 v[4:5], v[90:93], off
	v_lshl_add_u64 v[4:5], v[4:5], 0, s[14:15]
	global_load_dwordx4 v[82:85], v[6:7], off offset:-16
	global_load_dwordx4 v[86:89], v[6:7], off
	v_lshl_add_u64 v[6:7], v[6:7], 0, s[16:17]
	s_waitcnt vmcnt(12)
	v_lshlrev_b32_e32 v26, 16, v66
	v_and_b32_e32 v27, 0xffff0000, v66
	v_lshlrev_b32_e32 v28, 16, v67
	v_and_b32_e32 v29, 0xffff0000, v67
	v_lshlrev_b32_e32 v30, 16, v68
	v_and_b32_e32 v31, 0xffff0000, v68
	v_lshlrev_b32_e32 v32, 16, v69
	v_and_b32_e32 v33, 0xffff0000, v69
	v_lshlrev_b32_e32 v34, 16, v70
	v_and_b32_e32 v35, 0xffff0000, v70
	v_lshlrev_b32_e32 v36, 16, v71
	v_and_b32_e32 v37, 0xffff0000, v71
	v_lshlrev_b32_e32 v38, 16, v72
	v_and_b32_e32 v39, 0xffff0000, v72
	v_lshlrev_b32_e32 v40, 16, v73
	v_and_b32_e32 v41, 0xffff0000, v73
	v_pk_mul_f32 v[42:43], v[26:27], v[26:27]
	v_add_f32_e32 v1, v42, v43
	v_pk_mul_f32 v[42:43], v[28:29], v[28:29]
	v_add_f32_e32 v1, v42, v1
	v_add_f32_e32 v1, v43, v1
	v_pk_mul_f32 v[42:43], v[30:31], v[30:31]
	v_add_f32_e32 v1, v42, v1
	v_add_f32_e32 v1, v43, v1
	v_pk_mul_f32 v[42:43], v[32:33], v[32:33]
	v_add_f32_e32 v1, v42, v1
	v_add_f32_e32 v1, v43, v1
	v_pk_mul_f32 v[42:43], v[34:35], v[34:35]
	v_add_f32_e32 v1, v42, v1
	v_add_f32_e32 v1, v43, v1
	v_pk_mul_f32 v[42:43], v[36:37], v[36:37]
	v_add_f32_e32 v1, v42, v1
	v_add_f32_e32 v1, v43, v1
	v_pk_mul_f32 v[42:43], v[38:39], v[38:39]
	v_add_f32_e32 v1, v42, v1
	v_add_f32_e32 v1, v43, v1
	v_pk_mul_f32 v[42:43], v[40:41], v[40:41]
	v_add_f32_e32 v1, v42, v1
	v_add_f32_e32 v1, v43, v1
	ds_bpermute_b32 v16, v8, v1
	s_waitcnt lgkmcnt(0)
	v_add_f32_e32 v1, v1, v16
	ds_bpermute_b32 v16, v9, v1
	s_waitcnt lgkmcnt(0)
	v_add_f32_e32 v1, v1, v16
	ds_bpermute_b32 v16, v10, v1
	s_waitcnt lgkmcnt(0)
	v_add_f32_e32 v1, v1, v16
	ds_bpermute_b32 v16, v11, v1
	s_waitcnt lgkmcnt(0)
	v_add_f32_e32 v1, v1, v16
	ds_bpermute_b32 v16, v12, v1
	s_waitcnt lgkmcnt(0)
	v_add_f32_e32 v1, v1, v16
	ds_bpermute_b32 v16, v13, v1
	s_waitcnt lgkmcnt(0)
	v_add_f32_e32 v1, v1, v16
	v_fmamk_f32 v1, v1, 0x3a800000, v194
	v_mul_f32_e32 v16, 0x4b800000, v1
	v_cmp_gt_f32_e32 vcc, s83, v1
	s_nop 1
	v_cndmask_b32_e32 v1, v1, v16, vcc
	v_rsq_f32_e32 v1, v1
	s_nop 0
	v_mul_f32_e32 v16, 0x45800000, v1
	v_cndmask_b32_e32 v48, v1, v16, vcc
	v_pk_mul_f32 v[44:45], v[48:49], v[26:27] op_sel_hi:[0,1]
	v_pk_mul_f32 v[46:47], v[48:49], v[28:29] op_sel_hi:[0,1]
	v_pk_mul_f32 v[44:45], v[50:51], v[44:45]
	v_pk_mul_f32 v[46:47], v[52:53], v[46:47]
	global_store_dwordx4 v[4:5], v[44:47], off offset:-48
	v_pk_mul_f32 v[90:91], v[48:49], v[30:31] op_sel_hi:[0,1]
	v_pk_mul_f32 v[92:93], v[48:49], v[32:33] op_sel_hi:[0,1]
	v_pk_mul_f32 v[90:91], v[54:55], v[90:91]
	v_pk_mul_f32 v[92:93], v[56:57], v[92:93]
	global_store_dwordx4 v[4:5], v[90:93], off offset:-32
	v_pk_mul_f32 v[44:45], v[48:49], v[34:35] op_sel_hi:[0,1]
	v_pk_mul_f32 v[46:47], v[48:49], v[36:37] op_sel_hi:[0,1]
	v_pk_mul_f32 v[44:45], v[58:59], v[44:45]
	v_pk_mul_f32 v[46:47], v[60:61], v[46:47]
	global_store_dwordx4 v[4:5], v[44:47], off offset:-16
	v_pk_mul_f32 v[90:91], v[48:49], v[38:39] op_sel_hi:[0,1]
	v_pk_mul_f32 v[92:93], v[48:49], v[40:41] op_sel_hi:[0,1]
	v_pk_mul_f32 v[90:91], v[62:63], v[90:91]
	v_pk_mul_f32 v[92:93], v[64:65], v[92:93]
	global_store_dwordx4 v[4:5], v[90:93], off
	v_lshl_add_u64 v[4:5], v[4:5], 0, s[14:15]
	global_load_dwordx4 v[66:69], v[6:7], off offset:-16
	global_load_dwordx4 v[70:73], v[6:7], off
	v_lshl_add_u64 v[6:7], v[6:7], 0, s[16:17]
	s_waitcnt vmcnt(12)
	v_lshlrev_b32_e32 v26, 16, v74
	v_and_b32_e32 v27, 0xffff0000, v74
	v_lshlrev_b32_e32 v28, 16, v75
	v_and_b32_e32 v29, 0xffff0000, v75
	v_lshlrev_b32_e32 v30, 16, v76
	v_and_b32_e32 v31, 0xffff0000, v76
	v_lshlrev_b32_e32 v32, 16, v77
	v_and_b32_e32 v33, 0xffff0000, v77
	v_lshlrev_b32_e32 v34, 16, v78
	v_and_b32_e32 v35, 0xffff0000, v78
	v_lshlrev_b32_e32 v36, 16, v79
	v_and_b32_e32 v37, 0xffff0000, v79
	v_lshlrev_b32_e32 v38, 16, v80
	v_and_b32_e32 v39, 0xffff0000, v80
	v_lshlrev_b32_e32 v40, 16, v81
	v_and_b32_e32 v41, 0xffff0000, v81
	v_pk_mul_f32 v[42:43], v[26:27], v[26:27]
	v_add_f32_e32 v1, v42, v43
	v_pk_mul_f32 v[42:43], v[28:29], v[28:29]
	v_add_f32_e32 v1, v42, v1
	v_add_f32_e32 v1, v43, v1
	v_pk_mul_f32 v[42:43], v[30:31], v[30:31]
	v_add_f32_e32 v1, v42, v1
	v_add_f32_e32 v1, v43, v1
	v_pk_mul_f32 v[42:43], v[32:33], v[32:33]
	v_add_f32_e32 v1, v42, v1
	v_add_f32_e32 v1, v43, v1
	v_pk_mul_f32 v[42:43], v[34:35], v[34:35]
	v_add_f32_e32 v1, v42, v1
	v_add_f32_e32 v1, v43, v1
	v_pk_mul_f32 v[42:43], v[36:37], v[36:37]
	v_add_f32_e32 v1, v42, v1
	v_add_f32_e32 v1, v43, v1
	v_pk_mul_f32 v[42:43], v[38:39], v[38:39]
	v_add_f32_e32 v1, v42, v1
	v_add_f32_e32 v1, v43, v1
	v_pk_mul_f32 v[42:43], v[40:41], v[40:41]
	v_add_f32_e32 v1, v42, v1
	v_add_f32_e32 v1, v43, v1
	ds_bpermute_b32 v16, v8, v1
	s_waitcnt lgkmcnt(0)
	v_add_f32_e32 v1, v1, v16
	ds_bpermute_b32 v16, v9, v1
	s_waitcnt lgkmcnt(0)
	v_add_f32_e32 v1, v1, v16
	ds_bpermute_b32 v16, v10, v1
	s_waitcnt lgkmcnt(0)
	v_add_f32_e32 v1, v1, v16
	ds_bpermute_b32 v16, v11, v1
	s_waitcnt lgkmcnt(0)
	v_add_f32_e32 v1, v1, v16
	ds_bpermute_b32 v16, v12, v1
	s_waitcnt lgkmcnt(0)
	v_add_f32_e32 v1, v1, v16
	ds_bpermute_b32 v16, v13, v1
	s_waitcnt lgkmcnt(0)
	v_add_f32_e32 v1, v1, v16
	v_fmamk_f32 v1, v1, 0x3a800000, v194
	v_mul_f32_e32 v16, 0x4b800000, v1
	v_cmp_gt_f32_e32 vcc, s83, v1
	s_nop 1
	v_cndmask_b32_e32 v1, v1, v16, vcc
	v_rsq_f32_e32 v1, v1
	s_nop 0
	v_mul_f32_e32 v16, 0x45800000, v1
	v_cndmask_b32_e32 v48, v1, v16, vcc
	v_pk_mul_f32 v[44:45], v[48:49], v[26:27] op_sel_hi:[0,1]
	v_pk_mul_f32 v[46:47], v[48:49], v[28:29] op_sel_hi:[0,1]
	v_pk_mul_f32 v[44:45], v[50:51], v[44:45]
	v_pk_mul_f32 v[46:47], v[52:53], v[46:47]
	global_store_dwordx4 v[4:5], v[44:47], off offset:-48
	v_pk_mul_f32 v[90:91], v[48:49], v[30:31] op_sel_hi:[0,1]
	v_pk_mul_f32 v[92:93], v[48:49], v[32:33] op_sel_hi:[0,1]
	v_pk_mul_f32 v[90:91], v[54:55], v[90:91]
	v_pk_mul_f32 v[92:93], v[56:57], v[92:93]
	global_store_dwordx4 v[4:5], v[90:93], off offset:-32
	v_pk_mul_f32 v[44:45], v[48:49], v[34:35] op_sel_hi:[0,1]
	v_pk_mul_f32 v[46:47], v[48:49], v[36:37] op_sel_hi:[0,1]
	v_pk_mul_f32 v[44:45], v[58:59], v[44:45]
	v_pk_mul_f32 v[46:47], v[60:61], v[46:47]
	global_store_dwordx4 v[4:5], v[44:47], off offset:-16
	v_pk_mul_f32 v[90:91], v[48:49], v[38:39] op_sel_hi:[0,1]
	v_pk_mul_f32 v[92:93], v[48:49], v[40:41] op_sel_hi:[0,1]
	v_pk_mul_f32 v[90:91], v[62:63], v[90:91]
	v_pk_mul_f32 v[92:93], v[64:65], v[92:93]
	global_store_dwordx4 v[4:5], v[90:93], off
	v_lshl_add_u64 v[4:5], v[4:5], 0, s[14:15]
	global_load_dwordx4 v[74:77], v[6:7], off offset:-16
	global_load_dwordx4 v[78:81], v[6:7], off
	v_lshl_add_u64 v[6:7], v[6:7], 0, s[16:17]
	s_waitcnt vmcnt(12)
	v_lshlrev_b32_e32 v26, 16, v82
	v_and_b32_e32 v27, 0xffff0000, v82
	v_lshlrev_b32_e32 v28, 16, v83
	v_and_b32_e32 v29, 0xffff0000, v83
	v_lshlrev_b32_e32 v30, 16, v84
	v_and_b32_e32 v31, 0xffff0000, v84
	v_lshlrev_b32_e32 v32, 16, v85
	v_and_b32_e32 v33, 0xffff0000, v85
	v_lshlrev_b32_e32 v34, 16, v86
	v_and_b32_e32 v35, 0xffff0000, v86
	v_lshlrev_b32_e32 v36, 16, v87
	v_and_b32_e32 v37, 0xffff0000, v87
	v_lshlrev_b32_e32 v38, 16, v88
	v_and_b32_e32 v39, 0xffff0000, v88
	v_lshlrev_b32_e32 v40, 16, v89
	v_and_b32_e32 v41, 0xffff0000, v89
	v_pk_mul_f32 v[42:43], v[26:27], v[26:27]
	v_add_f32_e32 v1, v42, v43
	v_pk_mul_f32 v[42:43], v[28:29], v[28:29]
	v_add_f32_e32 v1, v42, v1
	v_add_f32_e32 v1, v43, v1
	v_pk_mul_f32 v[42:43], v[30:31], v[30:31]
	v_add_f32_e32 v1, v42, v1
	v_add_f32_e32 v1, v43, v1
	v_pk_mul_f32 v[42:43], v[32:33], v[32:33]
	v_add_f32_e32 v1, v42, v1
	v_add_f32_e32 v1, v43, v1
	v_pk_mul_f32 v[42:43], v[34:35], v[34:35]
	v_add_f32_e32 v1, v42, v1
	v_add_f32_e32 v1, v43, v1
	v_pk_mul_f32 v[42:43], v[36:37], v[36:37]
	v_add_f32_e32 v1, v42, v1
	v_add_f32_e32 v1, v43, v1
	v_pk_mul_f32 v[42:43], v[38:39], v[38:39]
	v_add_f32_e32 v1, v42, v1
	v_add_f32_e32 v1, v43, v1
	v_pk_mul_f32 v[42:43], v[40:41], v[40:41]
	v_add_f32_e32 v1, v42, v1
	v_add_f32_e32 v1, v43, v1
	ds_bpermute_b32 v16, v8, v1
	s_waitcnt lgkmcnt(0)
	v_add_f32_e32 v1, v1, v16
	ds_bpermute_b32 v16, v9, v1
	s_waitcnt lgkmcnt(0)
	v_add_f32_e32 v1, v1, v16
	ds_bpermute_b32 v16, v10, v1
	s_waitcnt lgkmcnt(0)
	v_add_f32_e32 v1, v1, v16
	ds_bpermute_b32 v16, v11, v1
	s_waitcnt lgkmcnt(0)
	v_add_f32_e32 v1, v1, v16
	ds_bpermute_b32 v16, v12, v1
	s_waitcnt lgkmcnt(0)
	v_add_f32_e32 v1, v1, v16
	ds_bpermute_b32 v16, v13, v1
	s_waitcnt lgkmcnt(0)
	v_add_f32_e32 v1, v1, v16
	v_fmamk_f32 v1, v1, 0x3a800000, v194
	v_mul_f32_e32 v16, 0x4b800000, v1
	v_cmp_gt_f32_e32 vcc, s83, v1
	s_nop 1
	v_cndmask_b32_e32 v1, v1, v16, vcc
	v_rsq_f32_e32 v1, v1
	s_nop 0
	v_mul_f32_e32 v16, 0x45800000, v1
	v_cndmask_b32_e32 v48, v1, v16, vcc
	v_pk_mul_f32 v[44:45], v[48:49], v[26:27] op_sel_hi:[0,1]
	v_pk_mul_f32 v[46:47], v[48:49], v[28:29] op_sel_hi:[0,1]
	v_pk_mul_f32 v[44:45], v[50:51], v[44:45]
	v_pk_mul_f32 v[46:47], v[52:53], v[46:47]
	global_store_dwordx4 v[4:5], v[44:47], off offset:-48
	v_pk_mul_f32 v[90:91], v[48:49], v[30:31] op_sel_hi:[0,1]
	v_pk_mul_f32 v[92:93], v[48:49], v[32:33] op_sel_hi:[0,1]
	v_pk_mul_f32 v[90:91], v[54:55], v[90:91]
	v_pk_mul_f32 v[92:93], v[56:57], v[92:93]
	global_store_dwordx4 v[4:5], v[90:93], off offset:-32
	v_pk_mul_f32 v[44:45], v[48:49], v[34:35] op_sel_hi:[0,1]
	v_pk_mul_f32 v[46:47], v[48:49], v[36:37] op_sel_hi:[0,1]
	v_pk_mul_f32 v[44:45], v[58:59], v[44:45]
	v_pk_mul_f32 v[46:47], v[60:61], v[46:47]
	global_store_dwordx4 v[4:5], v[44:47], off offset:-16
	v_pk_mul_f32 v[90:91], v[48:49], v[38:39] op_sel_hi:[0,1]
	v_pk_mul_f32 v[92:93], v[48:49], v[40:41] op_sel_hi:[0,1]
	v_pk_mul_f32 v[90:91], v[62:63], v[90:91]
	v_pk_mul_f32 v[92:93], v[64:65], v[92:93]
	global_store_dwordx4 v[4:5], v[90:93], off
	v_lshl_add_u64 v[4:5], v[4:5], 0, s[14:15]
	global_load_dwordx4 v[82:85], v[6:7], off offset:-16
	global_load_dwordx4 v[86:89], v[6:7], off
	v_lshl_add_u64 v[6:7], v[6:7], 0, s[16:17]
	s_waitcnt vmcnt(12)
	v_lshlrev_b32_e32 v26, 16, v66
	v_and_b32_e32 v27, 0xffff0000, v66
	v_lshlrev_b32_e32 v28, 16, v67
	v_and_b32_e32 v29, 0xffff0000, v67
	v_lshlrev_b32_e32 v30, 16, v68
	v_and_b32_e32 v31, 0xffff0000, v68
	v_lshlrev_b32_e32 v32, 16, v69
	v_and_b32_e32 v33, 0xffff0000, v69
	v_lshlrev_b32_e32 v34, 16, v70
	v_and_b32_e32 v35, 0xffff0000, v70
	v_lshlrev_b32_e32 v36, 16, v71
	v_and_b32_e32 v37, 0xffff0000, v71
	v_lshlrev_b32_e32 v38, 16, v72
	v_and_b32_e32 v39, 0xffff0000, v72
	v_lshlrev_b32_e32 v40, 16, v73
	v_and_b32_e32 v41, 0xffff0000, v73
	v_pk_mul_f32 v[42:43], v[26:27], v[26:27]
	v_add_f32_e32 v1, v42, v43
	v_pk_mul_f32 v[42:43], v[28:29], v[28:29]
	v_add_f32_e32 v1, v42, v1
	v_add_f32_e32 v1, v43, v1
	v_pk_mul_f32 v[42:43], v[30:31], v[30:31]
	v_add_f32_e32 v1, v42, v1
	v_add_f32_e32 v1, v43, v1
	v_pk_mul_f32 v[42:43], v[32:33], v[32:33]
	v_add_f32_e32 v1, v42, v1
	v_add_f32_e32 v1, v43, v1
	v_pk_mul_f32 v[42:43], v[34:35], v[34:35]
	v_add_f32_e32 v1, v42, v1
	v_add_f32_e32 v1, v43, v1
	v_pk_mul_f32 v[42:43], v[36:37], v[36:37]
	v_add_f32_e32 v1, v42, v1
	v_add_f32_e32 v1, v43, v1
	v_pk_mul_f32 v[42:43], v[38:39], v[38:39]
	v_add_f32_e32 v1, v42, v1
	v_add_f32_e32 v1, v43, v1
	v_pk_mul_f32 v[42:43], v[40:41], v[40:41]
	v_add_f32_e32 v1, v42, v1
	v_add_f32_e32 v1, v43, v1
	ds_bpermute_b32 v16, v8, v1
	s_waitcnt lgkmcnt(0)
	v_add_f32_e32 v1, v1, v16
	ds_bpermute_b32 v16, v9, v1
	s_waitcnt lgkmcnt(0)
	v_add_f32_e32 v1, v1, v16
	ds_bpermute_b32 v16, v10, v1
	s_waitcnt lgkmcnt(0)
	v_add_f32_e32 v1, v1, v16
	ds_bpermute_b32 v16, v11, v1
	s_waitcnt lgkmcnt(0)
	v_add_f32_e32 v1, v1, v16
	ds_bpermute_b32 v16, v12, v1
	s_waitcnt lgkmcnt(0)
	v_add_f32_e32 v1, v1, v16
	ds_bpermute_b32 v16, v13, v1
	s_waitcnt lgkmcnt(0)
	v_add_f32_e32 v1, v1, v16
	v_fmamk_f32 v1, v1, 0x3a800000, v194
	v_mul_f32_e32 v16, 0x4b800000, v1
	v_cmp_gt_f32_e32 vcc, s83, v1
	s_nop 1
	v_cndmask_b32_e32 v1, v1, v16, vcc
	v_rsq_f32_e32 v1, v1
	s_nop 0
	v_mul_f32_e32 v16, 0x45800000, v1
	v_cndmask_b32_e32 v48, v1, v16, vcc
	v_pk_mul_f32 v[44:45], v[48:49], v[26:27] op_sel_hi:[0,1]
	v_pk_mul_f32 v[46:47], v[48:49], v[28:29] op_sel_hi:[0,1]
	v_pk_mul_f32 v[44:45], v[50:51], v[44:45]
	v_pk_mul_f32 v[46:47], v[52:53], v[46:47]
	global_store_dwordx4 v[4:5], v[44:47], off offset:-48
	v_pk_mul_f32 v[90:91], v[48:49], v[30:31] op_sel_hi:[0,1]
	v_pk_mul_f32 v[92:93], v[48:49], v[32:33] op_sel_hi:[0,1]
	v_pk_mul_f32 v[90:91], v[54:55], v[90:91]
	v_pk_mul_f32 v[92:93], v[56:57], v[92:93]
	global_store_dwordx4 v[4:5], v[90:93], off offset:-32
	v_pk_mul_f32 v[44:45], v[48:49], v[34:35] op_sel_hi:[0,1]
	v_pk_mul_f32 v[46:47], v[48:49], v[36:37] op_sel_hi:[0,1]
	v_pk_mul_f32 v[44:45], v[58:59], v[44:45]
	v_pk_mul_f32 v[46:47], v[60:61], v[46:47]
	global_store_dwordx4 v[4:5], v[44:47], off offset:-16
	v_pk_mul_f32 v[90:91], v[48:49], v[38:39] op_sel_hi:[0,1]
	v_pk_mul_f32 v[92:93], v[48:49], v[40:41] op_sel_hi:[0,1]
	v_pk_mul_f32 v[90:91], v[62:63], v[90:91]
	v_pk_mul_f32 v[92:93], v[64:65], v[92:93]
	global_store_dwordx4 v[4:5], v[90:93], off
	v_lshl_add_u64 v[4:5], v[4:5], 0, s[14:15]
	global_load_dwordx4 v[66:69], v[6:7], off offset:-16
	global_load_dwordx4 v[70:73], v[6:7], off
	v_lshl_add_u64 v[6:7], v[6:7], 0, s[16:17]
	s_waitcnt vmcnt(12)
	v_lshlrev_b32_e32 v26, 16, v74
	v_and_b32_e32 v27, 0xffff0000, v74
	v_lshlrev_b32_e32 v28, 16, v75
	v_and_b32_e32 v29, 0xffff0000, v75
	v_lshlrev_b32_e32 v30, 16, v76
	v_and_b32_e32 v31, 0xffff0000, v76
	v_lshlrev_b32_e32 v32, 16, v77
	v_and_b32_e32 v33, 0xffff0000, v77
	v_lshlrev_b32_e32 v34, 16, v78
	v_and_b32_e32 v35, 0xffff0000, v78
	v_lshlrev_b32_e32 v36, 16, v79
	v_and_b32_e32 v37, 0xffff0000, v79
	v_lshlrev_b32_e32 v38, 16, v80
	v_and_b32_e32 v39, 0xffff0000, v80
	v_lshlrev_b32_e32 v40, 16, v81
	v_and_b32_e32 v41, 0xffff0000, v81
	v_pk_mul_f32 v[42:43], v[26:27], v[26:27]
	v_add_f32_e32 v1, v42, v43
	v_pk_mul_f32 v[42:43], v[28:29], v[28:29]
	v_add_f32_e32 v1, v42, v1
	v_add_f32_e32 v1, v43, v1
	v_pk_mul_f32 v[42:43], v[30:31], v[30:31]
	v_add_f32_e32 v1, v42, v1
	v_add_f32_e32 v1, v43, v1
	v_pk_mul_f32 v[42:43], v[32:33], v[32:33]
	v_add_f32_e32 v1, v42, v1
	v_add_f32_e32 v1, v43, v1
	v_pk_mul_f32 v[42:43], v[34:35], v[34:35]
	v_add_f32_e32 v1, v42, v1
	v_add_f32_e32 v1, v43, v1
	v_pk_mul_f32 v[42:43], v[36:37], v[36:37]
	v_add_f32_e32 v1, v42, v1
	v_add_f32_e32 v1, v43, v1
	v_pk_mul_f32 v[42:43], v[38:39], v[38:39]
	v_add_f32_e32 v1, v42, v1
	v_add_f32_e32 v1, v43, v1
	v_pk_mul_f32 v[42:43], v[40:41], v[40:41]
	v_add_f32_e32 v1, v42, v1
	v_add_f32_e32 v1, v43, v1
	ds_bpermute_b32 v16, v8, v1
	s_waitcnt lgkmcnt(0)
	v_add_f32_e32 v1, v1, v16
	ds_bpermute_b32 v16, v9, v1
	s_waitcnt lgkmcnt(0)
	v_add_f32_e32 v1, v1, v16
	ds_bpermute_b32 v16, v10, v1
	s_waitcnt lgkmcnt(0)
	v_add_f32_e32 v1, v1, v16
	ds_bpermute_b32 v16, v11, v1
	s_waitcnt lgkmcnt(0)
	v_add_f32_e32 v1, v1, v16
	ds_bpermute_b32 v16, v12, v1
	s_waitcnt lgkmcnt(0)
	v_add_f32_e32 v1, v1, v16
	ds_bpermute_b32 v16, v13, v1
	s_waitcnt lgkmcnt(0)
	v_add_f32_e32 v1, v1, v16
	v_fmamk_f32 v1, v1, 0x3a800000, v194
	v_mul_f32_e32 v16, 0x4b800000, v1
	v_cmp_gt_f32_e32 vcc, s83, v1
	s_nop 1
	v_cndmask_b32_e32 v1, v1, v16, vcc
	v_rsq_f32_e32 v1, v1
	s_nop 0
	v_mul_f32_e32 v16, 0x45800000, v1
	v_cndmask_b32_e32 v48, v1, v16, vcc
	v_pk_mul_f32 v[44:45], v[48:49], v[26:27] op_sel_hi:[0,1]
	v_pk_mul_f32 v[46:47], v[48:49], v[28:29] op_sel_hi:[0,1]
	v_pk_mul_f32 v[44:45], v[50:51], v[44:45]
	v_pk_mul_f32 v[46:47], v[52:53], v[46:47]
	global_store_dwordx4 v[4:5], v[44:47], off offset:-48
	v_pk_mul_f32 v[90:91], v[48:49], v[30:31] op_sel_hi:[0,1]
	v_pk_mul_f32 v[92:93], v[48:49], v[32:33] op_sel_hi:[0,1]
	v_pk_mul_f32 v[90:91], v[54:55], v[90:91]
	v_pk_mul_f32 v[92:93], v[56:57], v[92:93]
	global_store_dwordx4 v[4:5], v[90:93], off offset:-32
	v_pk_mul_f32 v[44:45], v[48:49], v[34:35] op_sel_hi:[0,1]
	v_pk_mul_f32 v[46:47], v[48:49], v[36:37] op_sel_hi:[0,1]
	v_pk_mul_f32 v[44:45], v[58:59], v[44:45]
	v_pk_mul_f32 v[46:47], v[60:61], v[46:47]
	global_store_dwordx4 v[4:5], v[44:47], off offset:-16
	v_pk_mul_f32 v[90:91], v[48:49], v[38:39] op_sel_hi:[0,1]
	v_pk_mul_f32 v[92:93], v[48:49], v[40:41] op_sel_hi:[0,1]
	v_pk_mul_f32 v[90:91], v[62:63], v[90:91]
	v_pk_mul_f32 v[92:93], v[64:65], v[92:93]
	global_store_dwordx4 v[4:5], v[90:93], off
	v_lshl_add_u64 v[4:5], v[4:5], 0, s[14:15]
	global_load_dwordx4 v[74:77], v[6:7], off offset:-16
	global_load_dwordx4 v[78:81], v[6:7], off
	v_lshl_add_u64 v[6:7], v[6:7], 0, s[16:17]
	s_waitcnt vmcnt(12)
	v_lshlrev_b32_e32 v26, 16, v82
	v_and_b32_e32 v27, 0xffff0000, v82
	v_lshlrev_b32_e32 v28, 16, v83
	v_and_b32_e32 v29, 0xffff0000, v83
	v_lshlrev_b32_e32 v30, 16, v84
	v_and_b32_e32 v31, 0xffff0000, v84
	v_lshlrev_b32_e32 v32, 16, v85
	v_and_b32_e32 v33, 0xffff0000, v85
	v_lshlrev_b32_e32 v34, 16, v86
	v_and_b32_e32 v35, 0xffff0000, v86
	v_lshlrev_b32_e32 v36, 16, v87
	v_and_b32_e32 v37, 0xffff0000, v87
	v_lshlrev_b32_e32 v38, 16, v88
	v_and_b32_e32 v39, 0xffff0000, v88
	v_lshlrev_b32_e32 v40, 16, v89
	v_and_b32_e32 v41, 0xffff0000, v89
	v_pk_mul_f32 v[42:43], v[26:27], v[26:27]
	v_add_f32_e32 v1, v42, v43
	v_pk_mul_f32 v[42:43], v[28:29], v[28:29]
	v_add_f32_e32 v1, v42, v1
	v_add_f32_e32 v1, v43, v1
	v_pk_mul_f32 v[42:43], v[30:31], v[30:31]
	v_add_f32_e32 v1, v42, v1
	v_add_f32_e32 v1, v43, v1
	v_pk_mul_f32 v[42:43], v[32:33], v[32:33]
	v_add_f32_e32 v1, v42, v1
	v_add_f32_e32 v1, v43, v1
	v_pk_mul_f32 v[42:43], v[34:35], v[34:35]
	v_add_f32_e32 v1, v42, v1
	v_add_f32_e32 v1, v43, v1
	v_pk_mul_f32 v[42:43], v[36:37], v[36:37]
	v_add_f32_e32 v1, v42, v1
	v_add_f32_e32 v1, v43, v1
	v_pk_mul_f32 v[42:43], v[38:39], v[38:39]
	v_add_f32_e32 v1, v42, v1
	v_add_f32_e32 v1, v43, v1
	v_pk_mul_f32 v[42:43], v[40:41], v[40:41]
	v_add_f32_e32 v1, v42, v1
	v_add_f32_e32 v1, v43, v1
	ds_bpermute_b32 v16, v8, v1
	s_waitcnt lgkmcnt(0)
	v_add_f32_e32 v1, v1, v16
	ds_bpermute_b32 v16, v9, v1
	s_waitcnt lgkmcnt(0)
	v_add_f32_e32 v1, v1, v16
	ds_bpermute_b32 v16, v10, v1
	s_waitcnt lgkmcnt(0)
	v_add_f32_e32 v1, v1, v16
	ds_bpermute_b32 v16, v11, v1
	s_waitcnt lgkmcnt(0)
	v_add_f32_e32 v1, v1, v16
	ds_bpermute_b32 v16, v12, v1
	s_waitcnt lgkmcnt(0)
	v_add_f32_e32 v1, v1, v16
	ds_bpermute_b32 v16, v13, v1
	s_waitcnt lgkmcnt(0)
	v_add_f32_e32 v1, v1, v16
	v_fmamk_f32 v1, v1, 0x3a800000, v194
	v_mul_f32_e32 v16, 0x4b800000, v1
	v_cmp_gt_f32_e32 vcc, s83, v1
	s_nop 1
	v_cndmask_b32_e32 v1, v1, v16, vcc
	v_rsq_f32_e32 v1, v1
	s_nop 0
	v_mul_f32_e32 v16, 0x45800000, v1
	v_cndmask_b32_e32 v48, v1, v16, vcc
	v_pk_mul_f32 v[44:45], v[48:49], v[26:27] op_sel_hi:[0,1]
	v_pk_mul_f32 v[46:47], v[48:49], v[28:29] op_sel_hi:[0,1]
	v_pk_mul_f32 v[44:45], v[50:51], v[44:45]
	v_pk_mul_f32 v[46:47], v[52:53], v[46:47]
	global_store_dwordx4 v[4:5], v[44:47], off offset:-48
	v_pk_mul_f32 v[90:91], v[48:49], v[30:31] op_sel_hi:[0,1]
	v_pk_mul_f32 v[92:93], v[48:49], v[32:33] op_sel_hi:[0,1]
	v_pk_mul_f32 v[90:91], v[54:55], v[90:91]
	v_pk_mul_f32 v[92:93], v[56:57], v[92:93]
	global_store_dwordx4 v[4:5], v[90:93], off offset:-32
	v_pk_mul_f32 v[44:45], v[48:49], v[34:35] op_sel_hi:[0,1]
	v_pk_mul_f32 v[46:47], v[48:49], v[36:37] op_sel_hi:[0,1]
	v_pk_mul_f32 v[44:45], v[58:59], v[44:45]
	v_pk_mul_f32 v[46:47], v[60:61], v[46:47]
	global_store_dwordx4 v[4:5], v[44:47], off offset:-16
	v_pk_mul_f32 v[90:91], v[48:49], v[38:39] op_sel_hi:[0,1]
	v_pk_mul_f32 v[92:93], v[48:49], v[40:41] op_sel_hi:[0,1]
	v_pk_mul_f32 v[90:91], v[62:63], v[90:91]
	v_pk_mul_f32 v[92:93], v[64:65], v[92:93]
	global_store_dwordx4 v[4:5], v[90:93], off
	v_lshl_add_u64 v[4:5], v[4:5], 0, s[14:15]
	global_load_dwordx4 v[82:85], v[6:7], off offset:-16
	global_load_dwordx4 v[86:89], v[6:7], off
	v_lshl_add_u64 v[6:7], v[6:7], 0, s[16:17]
	s_waitcnt vmcnt(12)
	v_lshlrev_b32_e32 v26, 16, v66
	v_and_b32_e32 v27, 0xffff0000, v66
	v_lshlrev_b32_e32 v28, 16, v67
	v_and_b32_e32 v29, 0xffff0000, v67
	v_lshlrev_b32_e32 v30, 16, v68
	v_and_b32_e32 v31, 0xffff0000, v68
	v_lshlrev_b32_e32 v32, 16, v69
	v_and_b32_e32 v33, 0xffff0000, v69
	v_lshlrev_b32_e32 v34, 16, v70
	v_and_b32_e32 v35, 0xffff0000, v70
	v_lshlrev_b32_e32 v36, 16, v71
	v_and_b32_e32 v37, 0xffff0000, v71
	v_lshlrev_b32_e32 v38, 16, v72
	v_and_b32_e32 v39, 0xffff0000, v72
	v_lshlrev_b32_e32 v40, 16, v73
	v_and_b32_e32 v41, 0xffff0000, v73
	v_pk_mul_f32 v[42:43], v[26:27], v[26:27]
	v_add_f32_e32 v1, v42, v43
	v_pk_mul_f32 v[42:43], v[28:29], v[28:29]
	v_add_f32_e32 v1, v42, v1
	v_add_f32_e32 v1, v43, v1
	v_pk_mul_f32 v[42:43], v[30:31], v[30:31]
	v_add_f32_e32 v1, v42, v1
	v_add_f32_e32 v1, v43, v1
	v_pk_mul_f32 v[42:43], v[32:33], v[32:33]
	v_add_f32_e32 v1, v42, v1
	v_add_f32_e32 v1, v43, v1
	v_pk_mul_f32 v[42:43], v[34:35], v[34:35]
	v_add_f32_e32 v1, v42, v1
	v_add_f32_e32 v1, v43, v1
	v_pk_mul_f32 v[42:43], v[36:37], v[36:37]
	v_add_f32_e32 v1, v42, v1
	v_add_f32_e32 v1, v43, v1
	v_pk_mul_f32 v[42:43], v[38:39], v[38:39]
	v_add_f32_e32 v1, v42, v1
	v_add_f32_e32 v1, v43, v1
	v_pk_mul_f32 v[42:43], v[40:41], v[40:41]
	v_add_f32_e32 v1, v42, v1
	v_add_f32_e32 v1, v43, v1
	ds_bpermute_b32 v16, v8, v1
	s_waitcnt lgkmcnt(0)
	v_add_f32_e32 v1, v1, v16
	ds_bpermute_b32 v16, v9, v1
	s_waitcnt lgkmcnt(0)
	v_add_f32_e32 v1, v1, v16
	ds_bpermute_b32 v16, v10, v1
	s_waitcnt lgkmcnt(0)
	v_add_f32_e32 v1, v1, v16
	ds_bpermute_b32 v16, v11, v1
	s_waitcnt lgkmcnt(0)
	v_add_f32_e32 v1, v1, v16
	ds_bpermute_b32 v16, v12, v1
	s_waitcnt lgkmcnt(0)
	v_add_f32_e32 v1, v1, v16
	ds_bpermute_b32 v16, v13, v1
	s_waitcnt lgkmcnt(0)
	v_add_f32_e32 v1, v1, v16
	v_fmamk_f32 v1, v1, 0x3a800000, v194
	v_mul_f32_e32 v16, 0x4b800000, v1
	v_cmp_gt_f32_e32 vcc, s83, v1
	s_nop 1
	v_cndmask_b32_e32 v1, v1, v16, vcc
	v_rsq_f32_e32 v1, v1
	s_nop 0
	v_mul_f32_e32 v16, 0x45800000, v1
	v_cndmask_b32_e32 v48, v1, v16, vcc
	v_pk_mul_f32 v[44:45], v[48:49], v[26:27] op_sel_hi:[0,1]
	v_pk_mul_f32 v[46:47], v[48:49], v[28:29] op_sel_hi:[0,1]
	v_pk_mul_f32 v[44:45], v[50:51], v[44:45]
	v_pk_mul_f32 v[46:47], v[52:53], v[46:47]
	global_store_dwordx4 v[4:5], v[44:47], off offset:-48
	v_pk_mul_f32 v[90:91], v[48:49], v[30:31] op_sel_hi:[0,1]
	v_pk_mul_f32 v[92:93], v[48:49], v[32:33] op_sel_hi:[0,1]
	v_pk_mul_f32 v[90:91], v[54:55], v[90:91]
	v_pk_mul_f32 v[92:93], v[56:57], v[92:93]
	global_store_dwordx4 v[4:5], v[90:93], off offset:-32
	v_pk_mul_f32 v[44:45], v[48:49], v[34:35] op_sel_hi:[0,1]
	v_pk_mul_f32 v[46:47], v[48:49], v[36:37] op_sel_hi:[0,1]
	v_pk_mul_f32 v[44:45], v[58:59], v[44:45]
	v_pk_mul_f32 v[46:47], v[60:61], v[46:47]
	global_store_dwordx4 v[4:5], v[44:47], off offset:-16
	v_pk_mul_f32 v[90:91], v[48:49], v[38:39] op_sel_hi:[0,1]
	v_pk_mul_f32 v[92:93], v[48:49], v[40:41] op_sel_hi:[0,1]
	v_pk_mul_f32 v[90:91], v[62:63], v[90:91]
	v_pk_mul_f32 v[92:93], v[64:65], v[92:93]
	global_store_dwordx4 v[4:5], v[90:93], off
	v_lshl_add_u64 v[4:5], v[4:5], 0, s[14:15]
	global_load_dwordx4 v[66:69], v[6:7], off offset:-16
	global_load_dwordx4 v[70:73], v[6:7], off
	v_lshl_add_u64 v[6:7], v[6:7], 0, s[16:17]
	s_waitcnt vmcnt(12)
	v_lshlrev_b32_e32 v26, 16, v74
	v_and_b32_e32 v27, 0xffff0000, v74
	v_lshlrev_b32_e32 v28, 16, v75
	v_and_b32_e32 v29, 0xffff0000, v75
	v_lshlrev_b32_e32 v30, 16, v76
	v_and_b32_e32 v31, 0xffff0000, v76
	v_lshlrev_b32_e32 v32, 16, v77
	v_and_b32_e32 v33, 0xffff0000, v77
	v_lshlrev_b32_e32 v34, 16, v78
	v_and_b32_e32 v35, 0xffff0000, v78
	v_lshlrev_b32_e32 v36, 16, v79
	v_and_b32_e32 v37, 0xffff0000, v79
	v_lshlrev_b32_e32 v38, 16, v80
	v_and_b32_e32 v39, 0xffff0000, v80
	v_lshlrev_b32_e32 v40, 16, v81
	v_and_b32_e32 v41, 0xffff0000, v81
	v_pk_mul_f32 v[42:43], v[26:27], v[26:27]
	v_add_f32_e32 v1, v42, v43
	v_pk_mul_f32 v[42:43], v[28:29], v[28:29]
	v_add_f32_e32 v1, v42, v1
	v_add_f32_e32 v1, v43, v1
	v_pk_mul_f32 v[42:43], v[30:31], v[30:31]
	v_add_f32_e32 v1, v42, v1
	v_add_f32_e32 v1, v43, v1
	v_pk_mul_f32 v[42:43], v[32:33], v[32:33]
	v_add_f32_e32 v1, v42, v1
	v_add_f32_e32 v1, v43, v1
	v_pk_mul_f32 v[42:43], v[34:35], v[34:35]
	v_add_f32_e32 v1, v42, v1
	v_add_f32_e32 v1, v43, v1
	v_pk_mul_f32 v[42:43], v[36:37], v[36:37]
	v_add_f32_e32 v1, v42, v1
	v_add_f32_e32 v1, v43, v1
	v_pk_mul_f32 v[42:43], v[38:39], v[38:39]
	v_add_f32_e32 v1, v42, v1
	v_add_f32_e32 v1, v43, v1
	v_pk_mul_f32 v[42:43], v[40:41], v[40:41]
	v_add_f32_e32 v1, v42, v1
	v_add_f32_e32 v1, v43, v1
	ds_bpermute_b32 v16, v8, v1
	s_waitcnt lgkmcnt(0)
	v_add_f32_e32 v1, v1, v16
	ds_bpermute_b32 v16, v9, v1
	s_waitcnt lgkmcnt(0)
	v_add_f32_e32 v1, v1, v16
	ds_bpermute_b32 v16, v10, v1
	s_waitcnt lgkmcnt(0)
	v_add_f32_e32 v1, v1, v16
	ds_bpermute_b32 v16, v11, v1
	s_waitcnt lgkmcnt(0)
	v_add_f32_e32 v1, v1, v16
	ds_bpermute_b32 v16, v12, v1
	s_waitcnt lgkmcnt(0)
	v_add_f32_e32 v1, v1, v16
	ds_bpermute_b32 v16, v13, v1
	s_waitcnt lgkmcnt(0)
	v_add_f32_e32 v1, v1, v16
	v_fmamk_f32 v1, v1, 0x3a800000, v194
	v_mul_f32_e32 v16, 0x4b800000, v1
	v_cmp_gt_f32_e32 vcc, s83, v1
	s_nop 1
	v_cndmask_b32_e32 v1, v1, v16, vcc
	v_rsq_f32_e32 v1, v1
	s_nop 0
	v_mul_f32_e32 v16, 0x45800000, v1
	v_cndmask_b32_e32 v48, v1, v16, vcc
	v_pk_mul_f32 v[44:45], v[48:49], v[26:27] op_sel_hi:[0,1]
	v_pk_mul_f32 v[46:47], v[48:49], v[28:29] op_sel_hi:[0,1]
	v_pk_mul_f32 v[44:45], v[50:51], v[44:45]
	v_pk_mul_f32 v[46:47], v[52:53], v[46:47]
	global_store_dwordx4 v[4:5], v[44:47], off offset:-48
	v_pk_mul_f32 v[90:91], v[48:49], v[30:31] op_sel_hi:[0,1]
	v_pk_mul_f32 v[92:93], v[48:49], v[32:33] op_sel_hi:[0,1]
	v_pk_mul_f32 v[90:91], v[54:55], v[90:91]
	v_pk_mul_f32 v[92:93], v[56:57], v[92:93]
	global_store_dwordx4 v[4:5], v[90:93], off offset:-32
	v_pk_mul_f32 v[44:45], v[48:49], v[34:35] op_sel_hi:[0,1]
	v_pk_mul_f32 v[46:47], v[48:49], v[36:37] op_sel_hi:[0,1]
	v_pk_mul_f32 v[44:45], v[58:59], v[44:45]
	v_pk_mul_f32 v[46:47], v[60:61], v[46:47]
	global_store_dwordx4 v[4:5], v[44:47], off offset:-16
	v_pk_mul_f32 v[90:91], v[48:49], v[38:39] op_sel_hi:[0,1]
	v_pk_mul_f32 v[92:93], v[48:49], v[40:41] op_sel_hi:[0,1]
	v_pk_mul_f32 v[90:91], v[62:63], v[90:91]
	v_pk_mul_f32 v[92:93], v[64:65], v[92:93]
	global_store_dwordx4 v[4:5], v[90:93], off
	v_lshl_add_u64 v[4:5], v[4:5], 0, s[14:15]
	global_load_dwordx4 v[74:77], v[6:7], off offset:-16
	global_load_dwordx4 v[78:81], v[6:7], off
	v_lshl_add_u64 v[6:7], v[6:7], 0, s[16:17]
	s_waitcnt vmcnt(12)
	v_lshlrev_b32_e32 v26, 16, v82
	v_and_b32_e32 v27, 0xffff0000, v82
	v_lshlrev_b32_e32 v28, 16, v83
	v_and_b32_e32 v29, 0xffff0000, v83
	v_lshlrev_b32_e32 v30, 16, v84
	v_and_b32_e32 v31, 0xffff0000, v84
	v_lshlrev_b32_e32 v32, 16, v85
	v_and_b32_e32 v33, 0xffff0000, v85
	v_lshlrev_b32_e32 v34, 16, v86
	v_and_b32_e32 v35, 0xffff0000, v86
	v_lshlrev_b32_e32 v36, 16, v87
	v_and_b32_e32 v37, 0xffff0000, v87
	v_lshlrev_b32_e32 v38, 16, v88
	v_and_b32_e32 v39, 0xffff0000, v88
	v_lshlrev_b32_e32 v40, 16, v89
	v_and_b32_e32 v41, 0xffff0000, v89
	v_pk_mul_f32 v[42:43], v[26:27], v[26:27]
	v_add_f32_e32 v1, v42, v43
	v_pk_mul_f32 v[42:43], v[28:29], v[28:29]
	v_add_f32_e32 v1, v42, v1
	v_add_f32_e32 v1, v43, v1
	v_pk_mul_f32 v[42:43], v[30:31], v[30:31]
	v_add_f32_e32 v1, v42, v1
	v_add_f32_e32 v1, v43, v1
	v_pk_mul_f32 v[42:43], v[32:33], v[32:33]
	v_add_f32_e32 v1, v42, v1
	v_add_f32_e32 v1, v43, v1
	v_pk_mul_f32 v[42:43], v[34:35], v[34:35]
	v_add_f32_e32 v1, v42, v1
	v_add_f32_e32 v1, v43, v1
	v_pk_mul_f32 v[42:43], v[36:37], v[36:37]
	v_add_f32_e32 v1, v42, v1
	v_add_f32_e32 v1, v43, v1
	v_pk_mul_f32 v[42:43], v[38:39], v[38:39]
	v_add_f32_e32 v1, v42, v1
	v_add_f32_e32 v1, v43, v1
	v_pk_mul_f32 v[42:43], v[40:41], v[40:41]
	v_add_f32_e32 v1, v42, v1
	v_add_f32_e32 v1, v43, v1
	ds_bpermute_b32 v16, v8, v1
	s_waitcnt lgkmcnt(0)
	v_add_f32_e32 v1, v1, v16
	ds_bpermute_b32 v16, v9, v1
	s_waitcnt lgkmcnt(0)
	v_add_f32_e32 v1, v1, v16
	ds_bpermute_b32 v16, v10, v1
	s_waitcnt lgkmcnt(0)
	v_add_f32_e32 v1, v1, v16
	ds_bpermute_b32 v16, v11, v1
	s_waitcnt lgkmcnt(0)
	v_add_f32_e32 v1, v1, v16
	ds_bpermute_b32 v16, v12, v1
	s_waitcnt lgkmcnt(0)
	v_add_f32_e32 v1, v1, v16
	ds_bpermute_b32 v16, v13, v1
	s_waitcnt lgkmcnt(0)
	v_add_f32_e32 v1, v1, v16
	v_fmamk_f32 v1, v1, 0x3a800000, v194
	v_mul_f32_e32 v16, 0x4b800000, v1
	v_cmp_gt_f32_e32 vcc, s83, v1
	s_nop 1
	v_cndmask_b32_e32 v1, v1, v16, vcc
	v_rsq_f32_e32 v1, v1
	s_nop 0
	v_mul_f32_e32 v16, 0x45800000, v1
	v_cndmask_b32_e32 v48, v1, v16, vcc
	v_pk_mul_f32 v[44:45], v[48:49], v[26:27] op_sel_hi:[0,1]
	v_pk_mul_f32 v[46:47], v[48:49], v[28:29] op_sel_hi:[0,1]
	v_pk_mul_f32 v[44:45], v[50:51], v[44:45]
	v_pk_mul_f32 v[46:47], v[52:53], v[46:47]
	global_store_dwordx4 v[4:5], v[44:47], off offset:-48
	v_pk_mul_f32 v[90:91], v[48:49], v[30:31] op_sel_hi:[0,1]
	v_pk_mul_f32 v[92:93], v[48:49], v[32:33] op_sel_hi:[0,1]
	v_pk_mul_f32 v[90:91], v[54:55], v[90:91]
	v_pk_mul_f32 v[92:93], v[56:57], v[92:93]
	global_store_dwordx4 v[4:5], v[90:93], off offset:-32
	v_pk_mul_f32 v[44:45], v[48:49], v[34:35] op_sel_hi:[0,1]
	v_pk_mul_f32 v[46:47], v[48:49], v[36:37] op_sel_hi:[0,1]
	v_pk_mul_f32 v[44:45], v[58:59], v[44:45]
	v_pk_mul_f32 v[46:47], v[60:61], v[46:47]
	global_store_dwordx4 v[4:5], v[44:47], off offset:-16
	v_pk_mul_f32 v[90:91], v[48:49], v[38:39] op_sel_hi:[0,1]
	v_pk_mul_f32 v[92:93], v[48:49], v[40:41] op_sel_hi:[0,1]
	v_pk_mul_f32 v[90:91], v[62:63], v[90:91]
	v_pk_mul_f32 v[92:93], v[64:65], v[92:93]
	global_store_dwordx4 v[4:5], v[90:93], off
	v_lshl_add_u64 v[4:5], v[4:5], 0, s[14:15]
	global_load_dwordx4 v[82:85], v[6:7], off offset:-16
	global_load_dwordx4 v[86:89], v[6:7], off
	v_lshl_add_u64 v[6:7], v[6:7], 0, s[16:17]
	s_waitcnt vmcnt(12)
	v_lshlrev_b32_e32 v26, 16, v66
	v_and_b32_e32 v27, 0xffff0000, v66
	v_lshlrev_b32_e32 v28, 16, v67
	v_and_b32_e32 v29, 0xffff0000, v67
	v_lshlrev_b32_e32 v30, 16, v68
	v_and_b32_e32 v31, 0xffff0000, v68
	v_lshlrev_b32_e32 v32, 16, v69
	v_and_b32_e32 v33, 0xffff0000, v69
	v_lshlrev_b32_e32 v34, 16, v70
	v_and_b32_e32 v35, 0xffff0000, v70
	v_lshlrev_b32_e32 v36, 16, v71
	v_and_b32_e32 v37, 0xffff0000, v71
	v_lshlrev_b32_e32 v38, 16, v72
	v_and_b32_e32 v39, 0xffff0000, v72
	v_lshlrev_b32_e32 v40, 16, v73
	v_and_b32_e32 v41, 0xffff0000, v73
	v_pk_mul_f32 v[42:43], v[26:27], v[26:27]
	v_add_f32_e32 v1, v42, v43
	v_pk_mul_f32 v[42:43], v[28:29], v[28:29]
	v_add_f32_e32 v1, v42, v1
	v_add_f32_e32 v1, v43, v1
	v_pk_mul_f32 v[42:43], v[30:31], v[30:31]
	v_add_f32_e32 v1, v42, v1
	v_add_f32_e32 v1, v43, v1
	v_pk_mul_f32 v[42:43], v[32:33], v[32:33]
	v_add_f32_e32 v1, v42, v1
	v_add_f32_e32 v1, v43, v1
	v_pk_mul_f32 v[42:43], v[34:35], v[34:35]
	v_add_f32_e32 v1, v42, v1
	v_add_f32_e32 v1, v43, v1
	v_pk_mul_f32 v[42:43], v[36:37], v[36:37]
	v_add_f32_e32 v1, v42, v1
	v_add_f32_e32 v1, v43, v1
	v_pk_mul_f32 v[42:43], v[38:39], v[38:39]
	v_add_f32_e32 v1, v42, v1
	v_add_f32_e32 v1, v43, v1
	v_pk_mul_f32 v[42:43], v[40:41], v[40:41]
	v_add_f32_e32 v1, v42, v1
	v_add_f32_e32 v1, v43, v1
	ds_bpermute_b32 v16, v8, v1
	s_waitcnt lgkmcnt(0)
	v_add_f32_e32 v1, v1, v16
	ds_bpermute_b32 v16, v9, v1
	s_waitcnt lgkmcnt(0)
	v_add_f32_e32 v1, v1, v16
	ds_bpermute_b32 v16, v10, v1
	s_waitcnt lgkmcnt(0)
	v_add_f32_e32 v1, v1, v16
	ds_bpermute_b32 v16, v11, v1
	s_waitcnt lgkmcnt(0)
	v_add_f32_e32 v1, v1, v16
	ds_bpermute_b32 v16, v12, v1
	s_waitcnt lgkmcnt(0)
	v_add_f32_e32 v1, v1, v16
	ds_bpermute_b32 v16, v13, v1
	s_waitcnt lgkmcnt(0)
	v_add_f32_e32 v1, v1, v16
	v_fmamk_f32 v1, v1, 0x3a800000, v194
	v_mul_f32_e32 v16, 0x4b800000, v1
	v_cmp_gt_f32_e32 vcc, s83, v1
	s_nop 1
	v_cndmask_b32_e32 v1, v1, v16, vcc
	v_rsq_f32_e32 v1, v1
	s_nop 0
	v_mul_f32_e32 v16, 0x45800000, v1
	v_cndmask_b32_e32 v48, v1, v16, vcc
	v_pk_mul_f32 v[44:45], v[48:49], v[26:27] op_sel_hi:[0,1]
	v_pk_mul_f32 v[46:47], v[48:49], v[28:29] op_sel_hi:[0,1]
	v_pk_mul_f32 v[44:45], v[50:51], v[44:45]
	v_pk_mul_f32 v[46:47], v[52:53], v[46:47]
	global_store_dwordx4 v[4:5], v[44:47], off offset:-48
	v_pk_mul_f32 v[90:91], v[48:49], v[30:31] op_sel_hi:[0,1]
	v_pk_mul_f32 v[92:93], v[48:49], v[32:33] op_sel_hi:[0,1]
	v_pk_mul_f32 v[90:91], v[54:55], v[90:91]
	v_pk_mul_f32 v[92:93], v[56:57], v[92:93]
	global_store_dwordx4 v[4:5], v[90:93], off offset:-32
	v_pk_mul_f32 v[44:45], v[48:49], v[34:35] op_sel_hi:[0,1]
	v_pk_mul_f32 v[46:47], v[48:49], v[36:37] op_sel_hi:[0,1]
	v_pk_mul_f32 v[44:45], v[58:59], v[44:45]
	v_pk_mul_f32 v[46:47], v[60:61], v[46:47]
	global_store_dwordx4 v[4:5], v[44:47], off offset:-16
	v_pk_mul_f32 v[90:91], v[48:49], v[38:39] op_sel_hi:[0,1]
	v_pk_mul_f32 v[92:93], v[48:49], v[40:41] op_sel_hi:[0,1]
	v_pk_mul_f32 v[90:91], v[62:63], v[90:91]
	v_pk_mul_f32 v[92:93], v[64:65], v[92:93]
	global_store_dwordx4 v[4:5], v[90:93], off
	v_lshl_add_u64 v[4:5], v[4:5], 0, s[14:15]
	global_load_dwordx4 v[66:69], v[6:7], off offset:-16
	global_load_dwordx4 v[70:73], v[6:7], off
	v_lshl_add_u64 v[6:7], v[6:7], 0, s[16:17]
	s_waitcnt vmcnt(12)
	v_lshlrev_b32_e32 v26, 16, v74
	v_and_b32_e32 v27, 0xffff0000, v74
	v_lshlrev_b32_e32 v28, 16, v75
	v_and_b32_e32 v29, 0xffff0000, v75
	v_lshlrev_b32_e32 v30, 16, v76
	v_and_b32_e32 v31, 0xffff0000, v76
	v_lshlrev_b32_e32 v32, 16, v77
	v_and_b32_e32 v33, 0xffff0000, v77
	v_lshlrev_b32_e32 v34, 16, v78
	v_and_b32_e32 v35, 0xffff0000, v78
	v_lshlrev_b32_e32 v36, 16, v79
	v_and_b32_e32 v37, 0xffff0000, v79
	v_lshlrev_b32_e32 v38, 16, v80
	v_and_b32_e32 v39, 0xffff0000, v80
	v_lshlrev_b32_e32 v40, 16, v81
	v_and_b32_e32 v41, 0xffff0000, v81
	v_pk_mul_f32 v[42:43], v[26:27], v[26:27]
	v_add_f32_e32 v1, v42, v43
	v_pk_mul_f32 v[42:43], v[28:29], v[28:29]
	v_add_f32_e32 v1, v42, v1
	v_add_f32_e32 v1, v43, v1
	v_pk_mul_f32 v[42:43], v[30:31], v[30:31]
	v_add_f32_e32 v1, v42, v1
	v_add_f32_e32 v1, v43, v1
	v_pk_mul_f32 v[42:43], v[32:33], v[32:33]
	v_add_f32_e32 v1, v42, v1
	v_add_f32_e32 v1, v43, v1
	v_pk_mul_f32 v[42:43], v[34:35], v[34:35]
	v_add_f32_e32 v1, v42, v1
	v_add_f32_e32 v1, v43, v1
	v_pk_mul_f32 v[42:43], v[36:37], v[36:37]
	v_add_f32_e32 v1, v42, v1
	v_add_f32_e32 v1, v43, v1
	v_pk_mul_f32 v[42:43], v[38:39], v[38:39]
	v_add_f32_e32 v1, v42, v1
	v_add_f32_e32 v1, v43, v1
	v_pk_mul_f32 v[42:43], v[40:41], v[40:41]
	v_add_f32_e32 v1, v42, v1
	v_add_f32_e32 v1, v43, v1
	ds_bpermute_b32 v16, v8, v1
	s_waitcnt lgkmcnt(0)
	v_add_f32_e32 v1, v1, v16
	ds_bpermute_b32 v16, v9, v1
	s_waitcnt lgkmcnt(0)
	v_add_f32_e32 v1, v1, v16
	ds_bpermute_b32 v16, v10, v1
	s_waitcnt lgkmcnt(0)
	v_add_f32_e32 v1, v1, v16
	ds_bpermute_b32 v16, v11, v1
	s_waitcnt lgkmcnt(0)
	v_add_f32_e32 v1, v1, v16
	ds_bpermute_b32 v16, v12, v1
	s_waitcnt lgkmcnt(0)
	v_add_f32_e32 v1, v1, v16
	ds_bpermute_b32 v16, v13, v1
	s_waitcnt lgkmcnt(0)
	v_add_f32_e32 v1, v1, v16
	v_fmamk_f32 v1, v1, 0x3a800000, v194
	v_mul_f32_e32 v16, 0x4b800000, v1
	v_cmp_gt_f32_e32 vcc, s83, v1
	s_nop 1
	v_cndmask_b32_e32 v1, v1, v16, vcc
	v_rsq_f32_e32 v1, v1
	s_nop 0
	v_mul_f32_e32 v16, 0x45800000, v1
	v_cndmask_b32_e32 v48, v1, v16, vcc
	v_pk_mul_f32 v[44:45], v[48:49], v[26:27] op_sel_hi:[0,1]
	v_pk_mul_f32 v[46:47], v[48:49], v[28:29] op_sel_hi:[0,1]
	v_pk_mul_f32 v[44:45], v[50:51], v[44:45]
	v_pk_mul_f32 v[46:47], v[52:53], v[46:47]
	global_store_dwordx4 v[4:5], v[44:47], off offset:-48
	v_pk_mul_f32 v[90:91], v[48:49], v[30:31] op_sel_hi:[0,1]
	v_pk_mul_f32 v[92:93], v[48:49], v[32:33] op_sel_hi:[0,1]
	v_pk_mul_f32 v[90:91], v[54:55], v[90:91]
	v_pk_mul_f32 v[92:93], v[56:57], v[92:93]
	global_store_dwordx4 v[4:5], v[90:93], off offset:-32
	v_pk_mul_f32 v[44:45], v[48:49], v[34:35] op_sel_hi:[0,1]
	v_pk_mul_f32 v[46:47], v[48:49], v[36:37] op_sel_hi:[0,1]
	v_pk_mul_f32 v[44:45], v[58:59], v[44:45]
	v_pk_mul_f32 v[46:47], v[60:61], v[46:47]
	global_store_dwordx4 v[4:5], v[44:47], off offset:-16
	v_pk_mul_f32 v[90:91], v[48:49], v[38:39] op_sel_hi:[0,1]
	v_pk_mul_f32 v[92:93], v[48:49], v[40:41] op_sel_hi:[0,1]
	v_pk_mul_f32 v[90:91], v[62:63], v[90:91]
	v_pk_mul_f32 v[92:93], v[64:65], v[92:93]
	global_store_dwordx4 v[4:5], v[90:93], off
	v_lshl_add_u64 v[4:5], v[4:5], 0, s[14:15]
	s_waitcnt vmcnt(10)
	v_lshlrev_b32_e32 v26, 16, v82
	v_and_b32_e32 v27, 0xffff0000, v82
	v_lshlrev_b32_e32 v28, 16, v83
	v_and_b32_e32 v29, 0xffff0000, v83
	v_lshlrev_b32_e32 v30, 16, v84
	v_and_b32_e32 v31, 0xffff0000, v84
	v_lshlrev_b32_e32 v32, 16, v85
	v_and_b32_e32 v33, 0xffff0000, v85
	v_lshlrev_b32_e32 v34, 16, v86
	v_and_b32_e32 v35, 0xffff0000, v86
	v_lshlrev_b32_e32 v36, 16, v87
	v_and_b32_e32 v37, 0xffff0000, v87
	v_lshlrev_b32_e32 v38, 16, v88
	v_and_b32_e32 v39, 0xffff0000, v88
	v_lshlrev_b32_e32 v40, 16, v89
	v_and_b32_e32 v41, 0xffff0000, v89
	v_pk_mul_f32 v[42:43], v[26:27], v[26:27]
	v_add_f32_e32 v1, v42, v43
	v_pk_mul_f32 v[42:43], v[28:29], v[28:29]
	v_add_f32_e32 v1, v42, v1
	v_add_f32_e32 v1, v43, v1
	v_pk_mul_f32 v[42:43], v[30:31], v[30:31]
	v_add_f32_e32 v1, v42, v1
	v_add_f32_e32 v1, v43, v1
	v_pk_mul_f32 v[42:43], v[32:33], v[32:33]
	v_add_f32_e32 v1, v42, v1
	v_add_f32_e32 v1, v43, v1
	v_pk_mul_f32 v[42:43], v[34:35], v[34:35]
	v_add_f32_e32 v1, v42, v1
	v_add_f32_e32 v1, v43, v1
	v_pk_mul_f32 v[42:43], v[36:37], v[36:37]
	v_add_f32_e32 v1, v42, v1
	v_add_f32_e32 v1, v43, v1
	v_pk_mul_f32 v[42:43], v[38:39], v[38:39]
	v_add_f32_e32 v1, v42, v1
	v_add_f32_e32 v1, v43, v1
	v_pk_mul_f32 v[42:43], v[40:41], v[40:41]
	v_add_f32_e32 v1, v42, v1
	v_add_f32_e32 v1, v43, v1
	ds_bpermute_b32 v16, v8, v1
	s_waitcnt lgkmcnt(0)
	v_add_f32_e32 v1, v1, v16
	ds_bpermute_b32 v16, v9, v1
	s_waitcnt lgkmcnt(0)
	v_add_f32_e32 v1, v1, v16
	ds_bpermute_b32 v16, v10, v1
	s_waitcnt lgkmcnt(0)
	v_add_f32_e32 v1, v1, v16
	ds_bpermute_b32 v16, v11, v1
	s_waitcnt lgkmcnt(0)
	v_add_f32_e32 v1, v1, v16
	ds_bpermute_b32 v16, v12, v1
	s_waitcnt lgkmcnt(0)
	v_add_f32_e32 v1, v1, v16
	ds_bpermute_b32 v16, v13, v1
	s_waitcnt lgkmcnt(0)
	v_add_f32_e32 v1, v1, v16
	v_fmamk_f32 v1, v1, 0x3a800000, v194
	v_mul_f32_e32 v16, 0x4b800000, v1
	v_cmp_gt_f32_e32 vcc, s83, v1
	s_nop 1
	v_cndmask_b32_e32 v1, v1, v16, vcc
	v_rsq_f32_e32 v1, v1
	s_nop 0
	v_mul_f32_e32 v16, 0x45800000, v1
	v_cndmask_b32_e32 v48, v1, v16, vcc
	v_pk_mul_f32 v[44:45], v[48:49], v[26:27] op_sel_hi:[0,1]
	v_pk_mul_f32 v[46:47], v[48:49], v[28:29] op_sel_hi:[0,1]
	v_pk_mul_f32 v[44:45], v[50:51], v[44:45]
	v_pk_mul_f32 v[46:47], v[52:53], v[46:47]
	global_store_dwordx4 v[4:5], v[44:47], off offset:-48
	v_pk_mul_f32 v[90:91], v[48:49], v[30:31] op_sel_hi:[0,1]
	v_pk_mul_f32 v[92:93], v[48:49], v[32:33] op_sel_hi:[0,1]
	v_pk_mul_f32 v[90:91], v[54:55], v[90:91]
	v_pk_mul_f32 v[92:93], v[56:57], v[92:93]
	global_store_dwordx4 v[4:5], v[90:93], off offset:-32
	v_pk_mul_f32 v[44:45], v[48:49], v[34:35] op_sel_hi:[0,1]
	v_pk_mul_f32 v[46:47], v[48:49], v[36:37] op_sel_hi:[0,1]
	v_pk_mul_f32 v[44:45], v[58:59], v[44:45]
	v_pk_mul_f32 v[46:47], v[60:61], v[46:47]
	global_store_dwordx4 v[4:5], v[44:47], off offset:-16
	v_pk_mul_f32 v[90:91], v[48:49], v[38:39] op_sel_hi:[0,1]
	v_pk_mul_f32 v[92:93], v[48:49], v[40:41] op_sel_hi:[0,1]
	v_pk_mul_f32 v[90:91], v[62:63], v[90:91]
	v_pk_mul_f32 v[92:93], v[64:65], v[92:93]
	global_store_dwordx4 v[4:5], v[90:93], off
	v_lshl_add_u64 v[4:5], v[4:5], 0, s[14:15]
	s_waitcnt vmcnt(8)
	v_lshlrev_b32_e32 v26, 16, v66
	v_and_b32_e32 v27, 0xffff0000, v66
	v_lshlrev_b32_e32 v28, 16, v67
	v_and_b32_e32 v29, 0xffff0000, v67
	v_lshlrev_b32_e32 v30, 16, v68
	v_and_b32_e32 v31, 0xffff0000, v68
	v_lshlrev_b32_e32 v32, 16, v69
	v_and_b32_e32 v33, 0xffff0000, v69
	v_lshlrev_b32_e32 v34, 16, v70
	v_and_b32_e32 v35, 0xffff0000, v70
	v_lshlrev_b32_e32 v36, 16, v71
	v_and_b32_e32 v37, 0xffff0000, v71
	v_lshlrev_b32_e32 v38, 16, v72
	v_and_b32_e32 v39, 0xffff0000, v72
	v_lshlrev_b32_e32 v40, 16, v73
	v_and_b32_e32 v41, 0xffff0000, v73
	v_pk_mul_f32 v[42:43], v[26:27], v[26:27]
	v_add_f32_e32 v1, v42, v43
	v_pk_mul_f32 v[42:43], v[28:29], v[28:29]
	v_add_f32_e32 v1, v42, v1
	v_add_f32_e32 v1, v43, v1
	v_pk_mul_f32 v[42:43], v[30:31], v[30:31]
	v_add_f32_e32 v1, v42, v1
	v_add_f32_e32 v1, v43, v1
	v_pk_mul_f32 v[42:43], v[32:33], v[32:33]
	v_add_f32_e32 v1, v42, v1
	v_add_f32_e32 v1, v43, v1
	v_pk_mul_f32 v[42:43], v[34:35], v[34:35]
	v_add_f32_e32 v1, v42, v1
	v_add_f32_e32 v1, v43, v1
	v_pk_mul_f32 v[42:43], v[36:37], v[36:37]
	v_add_f32_e32 v1, v42, v1
	v_add_f32_e32 v1, v43, v1
	v_pk_mul_f32 v[42:43], v[38:39], v[38:39]
	v_add_f32_e32 v1, v42, v1
	v_add_f32_e32 v1, v43, v1
	v_pk_mul_f32 v[42:43], v[40:41], v[40:41]
	v_add_f32_e32 v1, v42, v1
	v_add_f32_e32 v1, v43, v1
	ds_bpermute_b32 v16, v8, v1
	s_waitcnt lgkmcnt(0)
	v_add_f32_e32 v1, v1, v16
	ds_bpermute_b32 v16, v9, v1
	s_waitcnt lgkmcnt(0)
	v_add_f32_e32 v1, v1, v16
	ds_bpermute_b32 v16, v10, v1
	s_waitcnt lgkmcnt(0)
	v_add_f32_e32 v1, v1, v16
	ds_bpermute_b32 v16, v11, v1
	s_waitcnt lgkmcnt(0)
	v_add_f32_e32 v1, v1, v16
	ds_bpermute_b32 v16, v12, v1
	s_waitcnt lgkmcnt(0)
	v_add_f32_e32 v1, v1, v16
	ds_bpermute_b32 v16, v13, v1
	s_waitcnt lgkmcnt(0)
	v_add_f32_e32 v1, v1, v16
	v_fmamk_f32 v1, v1, 0x3a800000, v194
	v_mul_f32_e32 v16, 0x4b800000, v1
	v_cmp_gt_f32_e32 vcc, s83, v1
	s_nop 1
	v_cndmask_b32_e32 v1, v1, v16, vcc
	v_rsq_f32_e32 v1, v1
	s_nop 0
	v_mul_f32_e32 v16, 0x45800000, v1
	v_cndmask_b32_e32 v48, v1, v16, vcc
	v_pk_mul_f32 v[44:45], v[48:49], v[26:27] op_sel_hi:[0,1]
	v_pk_mul_f32 v[46:47], v[48:49], v[28:29] op_sel_hi:[0,1]
	v_pk_mul_f32 v[44:45], v[50:51], v[44:45]
	v_pk_mul_f32 v[46:47], v[52:53], v[46:47]
	global_store_dwordx4 v[4:5], v[44:47], off offset:-48
	v_pk_mul_f32 v[90:91], v[48:49], v[30:31] op_sel_hi:[0,1]
	v_pk_mul_f32 v[92:93], v[48:49], v[32:33] op_sel_hi:[0,1]
	v_pk_mul_f32 v[90:91], v[54:55], v[90:91]
	v_pk_mul_f32 v[92:93], v[56:57], v[92:93]
	global_store_dwordx4 v[4:5], v[90:93], off offset:-32
	v_pk_mul_f32 v[44:45], v[48:49], v[34:35] op_sel_hi:[0,1]
	v_pk_mul_f32 v[46:47], v[48:49], v[36:37] op_sel_hi:[0,1]
	v_pk_mul_f32 v[44:45], v[58:59], v[44:45]
	v_pk_mul_f32 v[46:47], v[60:61], v[46:47]
	global_store_dwordx4 v[4:5], v[44:47], off offset:-16
	v_pk_mul_f32 v[90:91], v[48:49], v[38:39] op_sel_hi:[0,1]
	v_pk_mul_f32 v[92:93], v[48:49], v[40:41] op_sel_hi:[0,1]
	v_pk_mul_f32 v[90:91], v[62:63], v[90:91]
	v_pk_mul_f32 v[92:93], v[64:65], v[92:93]
	global_store_dwordx4 v[4:5], v[90:93], off
	v_lshl_add_u64 v[4:5], v[4:5], 0, s[14:15]
	s_branch .LBB0_30
